# conversion item loop prefetch fix applied to the LIVE FFN-down-tail and layer-0 in-projection-tail instances (the earlier fix had landed in the G<=32 / G<=96 variants, which never execute at this grid
# baseline (speedup 1.0000x reference)
; __device__ __forceinline__ PItem p0_decode(const Args& a, int it) {
;     constexpr int I_IN = 16 * 96, I_OUT = 16 * 32, I_W1 = 16 * 88, I_W2 = 44 * 32, I_LAYER = I_IN + I_OUT + 2 * I_W1 + I_W2;
;     const int l = it / I_LAYER, e = l >> 1, odd = l & 1; int r = it % I_LAYER;
;     unsigned char* wl = a.ws + WS_W + (size_t)l * W_LAYER; float* cv = (float*)(a.ws + WS_CVEC) + (size_t)l * CVEC_LAYER;
;     PItem p;
;     if (r < I_IN) { const int kb = r / 96, nb = r % 96; p.W = (odd ? a.in[13] : a.in[5]) + (size_t)e * D * EIN; p.N = EIN; p.K = D; p.g = l > 0 ? a.in[21] + (size_t)(l - 1) * D : nullptr; p.be = l > 0 ? a.in[22] + (size_t)(l - 1) * D : nullptr;
;         p.WT = (bf16*)(wl + W_IN); p.drow0 = in_dst_row(32 * nb, odd); p.k0 = 64 * kb; p.n0 = 32 * nb; p.c1 = cv; p.c2 = cv + EIN; return p; } r -= I_IN;
;     if (r < I_OUT) { const int kb = r / 32, nb = r % 32; p.W = (odd ? a.in[15] : a.in[6]) + (size_t)e * D * D; p.N = D; p.K = D; p.g = nullptr; p.be = nullptr;
;         p.WT = (bf16*)(wl + W_OUT); p.drow0 = 32 * nb; p.k0 = 64 * kb; p.n0 = 32 * nb; p.c1 = nullptr; p.c2 = nullptr; return p; } r -= I_OUT;
;     if (r < 2 * I_W1) { const int second = r >= I_W1; if (second) r -= I_W1; const int kb = r / 88, nb = r % 88, n0 = 32 * nb; p.W = (second ? a.in[17] : a.in[16]) + (size_t)l * D * DFF; p.N = DFF; p.K = D;
;         p.g = a.in[19] + (size_t)l * D; p.be = a.in[20] + (size_t)l * D; p.WT = (bf16*)(wl + W_13); p.drow0 = 256 * (n0 >> 7) + (second ? 128 : 0) + (n0 & 127); p.k0 = 64 * kb; p.n0 = n0; p.c1 = cv + 2 * EIN; p.c2 = cv + 2 * EIN + NUP; return p; } r -= 2 * I_W1;
; __device__ __forceinline__ void p0_convert(const Frame& F, const Args& a, int it_lo, int it_hi, int widx, int nw, LAS float* scr) {
;     ...
;         for (int it = it0; it < itend; it += nw) {
;             const bool more = it + nw < itend;
;             PItem nxt = cur; f32x4 vn[8];
;             if (more) { nxt = p0_decode(a, it + nw); p0_item_load(nxt, F.lane, vn); }
.LBB0_520:
	v_mov_b64_e32 v[64:65], v[28:29]
	s_andn2_b64 vcc, exec, s[12:13]
	v_mov_b64_e32 v[62:63], v[26:27]
	s_mov_b64 s[18:19], s[26:27]
	s_mov_b64 s[20:21], s[34:35]
	s_mov_b32 s2, s41
	s_mov_b64 s[24:25], s[10:11]
	s_mov_b64 s[64:65], s[28:29]
	s_mov_b64 s[12:13], s[22:23]
	s_mov_b32 s14, s52
	s_mov_b32 s16, s60
	s_cbranch_vccz .LBB0_555
.LBB0_521:
	v_add_u32_e32 v232, s16, v67
	v_ashrrev_i32_e32 v233, 31, v232
	v_mov_b32_e32 v230, 1.0
	v_mov_b32_e32 v231, 0
	s_cmp_eq_u64 s[24:25], 0
	s_cbranch_scc1 .Lcv_ng_ip1
	v_lshl_add_u64 v[234:235], v[232:233], 2, s[24:25]
	global_load_dword v230, v[234:235], off
.Lcv_ng_ip1:
	s_cmp_eq_u64 s[64:65], 0
	s_cbranch_scc1 .Lcv_nb_ip1
	v_lshl_add_u64 v[234:235], v[232:233], 2, s[64:65]
	global_load_dword v231, v[234:235], off
.Lcv_nb_ip1:
	s_add_i32 s40, s40, s7
	v_readlane_b32 s0, v250, 27
	s_cmp_lt_i32 s40, s0
	s_cselect_b64 s[30:31], -1, 0
	s_cmp_ge_i32 s40, s0
	s_mov_b32 s52, s14
	s_mov_b32 s60, s16
	s_cbranch_scc1 .Lcv_np_ip1
	s_mul_hi_i32 s0, s40, 0x5397829d
	s_lshr_b32 s1, s0, 31
	s_ashr_i32 s0, s0, 11
	s_add_i32 s86, s0, s1
	s_mul_i32 s1, s86, 0x1880
	s_ashr_i32 s46, s86, 1
	s_and_b32 s0, s86, 1
	s_sub_i32 s1, s40, s1
	s_mul_i32 s11, s86, 0x1880000
	v_readlane_b32 s15, v253, 5
	s_mul_hi_i32 s10, s86, 0x1880000
	s_add_u32 s56, s15, s11
	v_readlane_b32 s11, v253, 6
	s_addc_u32 s57, s11, s10
	s_mul_i32 s11, s86, 0x11000
	v_readlane_b32 s15, v253, 7
	s_mul_hi_i32 s10, s86, 0x11000
	s_add_u32 s58, s15, s11
	v_readlane_b32 s11, v253, 8
	s_addc_u32 s59, s11, s10
	s_cmpk_gt_i32 s1, 0x5ff
	s_mov_b64 s[88:89], -1
	s_cbranch_scc0 .LBB0_531
	s_cmpk_gt_u32 s1, 0x7ff
	s_cbranch_scc0 .LBB0_528
	s_ashr_i32 s87, s86, 31
	s_mov_b64 s[10:11], -1
	s_cmpk_gt_u32 s1, 0x12ff
	s_mul_hi_i32 s15, s86, 0xb00000
	s_mul_i32 s17, s86, 0xb00000
	s_cbranch_scc0 .LBB0_526
	v_readlane_b32 s76, v253, 26
	v_readlane_b32 s77, v253, 27
	s_add_u32 s44, s76, s17
	s_addc_u32 s45, s77, s15
	s_add_u32 s22, s56, 0x1300000
	s_addc_u32 s23, s57, 0
	s_lshl_b32 s10, s1, 5
	s_and_b32 s52, s10, 0x3e0
	s_lshl_b32 s10, s1, 1
	s_and_b32 s10, s10, 0x7fffffc0
	v_readlane_b32 s78, v253, 28
	v_readlane_b32 s79, v253, 29
	v_readlane_b32 s80, v253, 30
	v_readlane_b32 s81, v253, 31
	v_readlane_b32 s82, v253, 32
	v_readlane_b32 s83, v253, 33
	s_add_i32 s60, s10, 0xffffda00
	s_mov_b64 s[10:11], 0

; #define GAS __attribute__((address_space(1)))
; #define LAS __attribute__((address_space(3)))
; #define LDS_WAIT() asm volatile("s_waitcnt lgkmcnt(0)" ::: "memory")
; __device__ __forceinline__ float bfr(float f) { return __uint_as_float(f2bf(f) << 16); }
; __device__ __forceinline__ void p0_item_load(const PItem& it, int lane, f32x4 (&v)[8]) {
; #pragma unroll
;     for (int i = 0; i < 8; ++i) v[i] = __builtin_nontemporal_load((const GAS f32x4*)(it.W + (size_t)(it.k0 + 8 * i + (lane >> 3)) * it.N + it.n0 + 4 * (lane & 7)));
; }
; __device__ __forceinline__ void p0_item_process(const PItem& it, int lane, const f32x4 (&v)[8], LAS float* scr) {
;     LAS float* gl = scr + 64 * 36 + 32; LAS float* bl = gl + 64;
;     ...
; #pragma unroll
;     for (int i = 0; i < 8; ++i) *(LAS f32x4*)(scr + SCR_ROW(8 * i + (lane >> 3)) + 4 * (lane & 7)) = v[i];
;     gl[lane] = it.g ? it.g[it.k0 + lane] : 1.f; bl[lane] = it.be ? it.be[it.k0 + lane] : 0.f;
;     LDS_WAIT(); asm volatile("" ::: "memory");
;     if (it.c1) { const int n = lane & 31, kh = lane >> 5; float s1 = 0.f, s2 = 0.f;
; #pragma unroll 8
;         for (int kk = 0; kk < 32; ++kk) { const int k = 32 * kh + kk; const float x = scr[SCR_ROW(k) + n]; s1 += bfr(gl[k] * x); s2 += bl[k] * x; }
;         s1 += __shfl_xor(s1, 32); s2 += __shfl_xor(s2, 32);
;         if (lane < 32) { atomicAdd(it.c1 + it.drow0 + n, s1); if (it.be) atomicAdd(it.c2 + it.drow0 + n, s2); } }
.LBB0_538:
	v_add_u32_e32 v2, s60, v70
	v_add_u32_e32 v10, s60, v72
	s_waitcnt lgkmcnt(0)
	v_add_u32_e32 v18, s60, v74
	v_add_u32_e32 v26, s60, v76
	v_ashrrev_i32_e32 v3, 31, v2
	v_ashrrev_i32_e32 v11, 31, v10
	v_ashrrev_i32_e32 v19, 31, v18
	v_ashrrev_i32_e32 v27, 31, v26
	v_mul_lo_u32 v4, s62, v3
	v_mul_lo_u32 v5, s63, v2
	v_mad_u64_u32 v[2:3], s[0:1], s62, v2, 0
	v_mul_lo_u32 v12, s62, v11
	v_mul_lo_u32 v13, s63, v10
	v_mad_u64_u32 v[10:11], s[46:47], s62, v10, 0
	v_mul_lo_u32 v20, s62, v19
	v_mul_lo_u32 v21, s63, v18
	v_mad_u64_u32 v[18:19], s[46:47], s62, v18, 0
	v_mul_lo_u32 v28, s62, v27
	v_mul_lo_u32 v29, s63, v26
	v_mad_u64_u32 v[26:27], s[46:47], s62, v26, 0
	v_add3_u32 v3, v3, v4, v5
	v_add_u32_e32 v4, s60, v71
	v_add3_u32 v11, v11, v12, v13
	v_add_u32_e32 v12, s60, v73
	v_add3_u32 v19, v19, v20, v21
	v_add_u32_e32 v20, s60, v75
	v_add3_u32 v27, v27, v28, v29
	v_add_u32_e32 v28, s60, v77
	v_ashrrev_i32_e32 v5, 31, v4
	v_ashrrev_i32_e32 v13, 31, v12
	v_ashrrev_i32_e32 v21, 31, v20
	v_ashrrev_i32_e32 v29, 31, v28
	v_mul_lo_u32 v6, s62, v5
	v_mul_lo_u32 v7, s63, v4
	v_mad_u64_u32 v[4:5], s[46:47], s62, v4, 0
	v_mul_lo_u32 v14, s62, v13
	v_mul_lo_u32 v15, s63, v12
	v_mad_u64_u32 v[12:13], s[46:47], s62, v12, 0
	v_mul_lo_u32 v22, s62, v21
	v_mul_lo_u32 v23, s63, v20
	v_mad_u64_u32 v[20:21], s[46:47], s62, v20, 0
	v_mul_lo_u32 v30, s62, v29
	v_mul_lo_u32 v31, s63, v28
	v_mad_u64_u32 v[28:29], s[46:47], s62, v28, 0
	s_ashr_i32 s49, s48, 31
	v_add3_u32 v5, v5, v6, v7
	v_add3_u32 v13, v13, v14, v15
	v_add3_u32 v21, v21, v22, v23
	v_add3_u32 v29, v29, v30, v31
	v_lshl_add_u64 v[2:3], v[2:3], 2, s[44:45]
	s_lshl_b64 s[0:1], s[48:49], 2
	v_lshl_add_u64 v[4:5], v[4:5], 2, s[44:45]
	v_lshl_add_u64 v[10:11], v[10:11], 2, s[44:45]
	v_lshl_add_u64 v[12:13], v[12:13], 2, s[44:45]
	v_lshl_add_u64 v[18:19], v[18:19], 2, s[44:45]
	v_lshl_add_u64 v[20:21], v[20:21], 2, s[44:45]
	v_lshl_add_u64 v[26:27], v[26:27], 2, s[44:45]
	v_lshl_add_u64 v[28:29], v[28:29], 2, s[44:45]
	v_lshl_add_u64 v[2:3], v[2:3], 0, s[0:1]
	v_mov_b32_e32 v69, v1
	v_lshl_add_u64 v[4:5], v[4:5], 0, s[0:1]
	v_lshl_add_u64 v[10:11], v[10:11], 0, s[0:1]
	v_lshl_add_u64 v[12:13], v[12:13], 0, s[0:1]
	v_lshl_add_u64 v[18:19], v[18:19], 0, s[0:1]
	v_lshl_add_u64 v[20:21], v[20:21], 0, s[0:1]
	v_lshl_add_u64 v[26:27], v[26:27], 0, s[0:1]
	v_lshl_add_u64 v[28:29], v[28:29], 0, s[0:1]
	v_lshl_add_u64 v[2:3], v[2:3], 0, v[68:69]
	v_lshl_add_u64 v[4:5], v[4:5], 0, v[68:69]
	v_lshl_add_u64 v[10:11], v[10:11], 0, v[68:69]
	v_lshl_add_u64 v[12:13], v[12:13], 0, v[68:69]
	v_lshl_add_u64 v[18:19], v[18:19], 0, v[68:69]
	v_lshl_add_u64 v[20:21], v[20:21], 0, v[68:69]
	v_lshl_add_u64 v[26:27], v[26:27], 0, v[68:69]
	v_lshl_add_u64 v[28:29], v[28:29], 0, v[68:69]
	global_load_dwordx4 v[6:9], v[2:3], off nt
	s_nop 0
	global_load_dwordx4 v[2:5], v[4:5], off nt
	s_nop 0
	global_load_dwordx4 v[14:17], v[10:11], off nt
	s_nop 0
	global_load_dwordx4 v[10:13], v[12:13], off nt
	s_nop 0
	global_load_dwordx4 v[22:25], v[18:19], off nt
	s_nop 0
	global_load_dwordx4 v[18:21], v[20:21], off nt
	s_nop 0
	global_load_dwordx4 v[30:33], v[26:27], off nt
	s_nop 0
	global_load_dwordx4 v[26:29], v[28:29], off nt
.LBB0_539:
	s_waitcnt vmcnt(15)
	ds_write_b128 v78, v[58:61]
	s_waitcnt vmcnt(14)
	ds_write_b128 v79, v[42:45] offset:16
	s_waitcnt vmcnt(13)
	ds_write_b128 v80, v[54:57] offset:32
	s_waitcnt vmcnt(12)
	ds_write_b128 v81, v[38:41] offset:48
	s_waitcnt vmcnt(11)
	ds_write_b128 v82, v[50:53] offset:64
	s_waitcnt vmcnt(10)
	ds_write_b128 v83, v[34:37] offset:80
	s_waitcnt vmcnt(9)
	ds_write_b128 v84, v[46:49] offset:96
	s_waitcnt vmcnt(8)
	ds_write_b128 v85, v[62:65] offset:112
	s_cmp_lg_u64 s[64:65], 0
	s_cselect_b64 s[24:25], -1, 0
	s_waitcnt vmcnt(8)
	ds_write_b32 v86, v230 offset:9344
	ds_write_b32 v86, v231 offset:9600
	s_waitcnt lgkmcnt(0)
	s_cmp_eq_u64 s[20:21], 0
	s_cbranch_scc1 .LBB0_552
	v_mov_b32_e32 v34, 0
	s_mov_b32 s0, 0
	v_mov_b32_e32 v36, v90
	v_mov_b32_e32 v35, v34
.LBB0_547:
	ds_read2_b32 v[50:51], v36 offset1:36
	v_add_u32_e32 v37, s0, v89
	ds_read_b128 v[38:41], v37
	ds_read_b128 v[42:45], v37 offset:16
	ds_read_b128 v[46:49], v37 offset:256
	s_add_i32 s0, s0, 32
	s_cmpk_eq_i32 s0, 0x80
	s_waitcnt lgkmcnt(2)
	v_mul_f32_e32 v38, v50, v38
	v_cvt_pk_bf16_f32 v38, v38, 0
	v_lshlrev_b32_e32 v53, 16, v38
	v_mul_f32_e32 v38, v51, v39
	s_waitcnt lgkmcnt(0)
	v_mul_f32_e32 v52, v50, v46
	v_cvt_pk_bf16_f32 v38, v38, 0
	v_pk_add_f32 v[34:35], v[34:35], v[52:53]
	v_lshlrev_b32_e32 v39, 16, v38
	v_mul_f32_e32 v38, v51, v47
	v_pk_add_f32 v[34:35], v[34:35], v[38:39]
	ds_read2_b32 v[38:39], v36 offset0:72 offset1:108
	s_waitcnt lgkmcnt(0)
	v_mul_f32_e32 v40, v38, v40
	v_cvt_pk_bf16_f32 v40, v40, 0
	v_lshlrev_b32_e32 v47, 16, v40
	v_mul_f32_e32 v46, v38, v48
	v_pk_add_f32 v[34:35], v[34:35], v[46:47]
	ds_read2_b32 v[46:47], v36 offset0:144 offset1:180
	v_mul_f32_e32 v38, v39, v41
	v_cvt_pk_bf16_f32 v38, v38, 0
	v_lshlrev_b32_e32 v41, 16, v38
	v_mul_f32_e32 v40, v39, v49
	s_waitcnt lgkmcnt(0)
	v_mul_f32_e32 v38, v46, v42
	v_cvt_pk_bf16_f32 v38, v38, 0
	v_pk_add_f32 v[34:35], v[34:35], v[40:41]
	v_lshlrev_b32_e32 v49, 16, v38
	ds_read_b128 v[38:41], v37 offset:272
	v_mul_f32_e32 v37, v47, v43
	v_cvt_pk_bf16_f32 v37, v37, 0
	v_lshlrev_b32_e32 v43, 16, v37
	s_waitcnt lgkmcnt(0)
	v_mul_f32_e32 v48, v46, v38
	v_mul_f32_e32 v42, v47, v39
	ds_read2_b32 v[38:39], v36 offset0:216 offset1:252
	v_pk_add_f32 v[34:35], v[34:35], v[48:49]
	v_add_u32_e32 v36, 0x490, v36
	v_pk_add_f32 v[34:35], v[34:35], v[42:43]
	s_waitcnt lgkmcnt(0)
	v_mul_f32_e32 v37, v38, v44
	v_cvt_pk_bf16_f32 v37, v37, 0
	v_lshlrev_b32_e32 v43, 16, v37
	v_mul_f32_e32 v37, v39, v45
	v_mul_f32_e32 v42, v38, v40
	v_cvt_pk_bf16_f32 v37, v37, 0
	v_pk_add_f32 v[34:35], v[34:35], v[42:43]
	v_lshlrev_b32_e32 v43, 16, v37
	v_mul_f32_e32 v42, v39, v41
	v_pk_add_f32 v[34:35], v[34:35], v[42:43]
	s_cbranch_scc0 .LBB0_547
	v_and_b32_e32 v37, 64, v221
	v_xor_b32_e32 v36, 32, v221
	v_add_u32_e32 v37, 64, v37
	v_cmp_lt_i32_e32 vcc, v36, v37
	s_nop 1
	v_cndmask_b32_e32 v36, v221, v36, vcc
	v_lshlrev_b32_e32 v36, 2, v36
	ds_bpermute_b32 v37, v36, v35
	ds_bpermute_b32 v36, v36, v34
	s_and_saveexec_b64 s[44:45], s[66:67]
	s_cbranch_execz .LBB0_551
	s_ashr_i32 s15, s14, 31
	s_lshl_b64 s[46:47], s[14:15], 2
	s_add_u32 s0, s20, s46
	s_waitcnt lgkmcnt(1)
	v_add_f32_e32 v37, v35, v37
	s_addc_u32 s1, s21, s47
	v_lshlrev_b32_e32 v35, 2, v66
	global_atomic_add_f32 v35, v37, s[0:1]
	s_andn2_b64 vcc, exec, s[24:25]
	s_cbranch_vccnz .LBB0_551
	s_add_u32 s0, s18, s46
	s_waitcnt lgkmcnt(0)
	v_add_f32_e32 v34, v34, v36
	s_addc_u32 s1, s19, s47
	global_atomic_add_f32 v35, v34, s[0:1]

; #define LAS __attribute__((address_space(3)))
; __device__ __forceinline__ PItem p0_decode(const Args& a, int it) {
;     ...
;     { const int kb = r / 32, nb = r % 32; p.W = a.in[18] + (size_t)l * DFF * D; p.N = D; p.K = DFF; p.g = nullptr; p.be = nullptr; p.WT = (bf16*)(wl + W_2); p.drow0 = 32 * nb; p.k0 = 64 * kb; p.n0 = 32 * nb; p.c1 = nullptr; p.c2 = nullptr; return p; }
; }
; __device__ __forceinline__ void p0_convert(const Frame& F, const Args& a, int it_lo, int it_hi, int widx, int nw, LAS float* scr) {
;     const int it0 = it_lo + widx, itend = it_hi;
;     if (it0 < itend) {
;         PItem cur = p0_decode(a, it0); f32x4 vc[8]; p0_item_load(cur, F.lane, vc);
;         for (int it = it0; it < itend; it += nw) {
;             const bool more = it + nw < itend;
;             PItem nxt = cur; f32x4 vn[8];
;             if (more) { nxt = p0_decode(a, it + nw); p0_item_load(nxt, F.lane, vn); }
;             p0_item_process(cur, F.lane, vc, scr);
.Lcv_np_ip1:
	s_waitcnt vmcnt(0)
	s_branch .LBB0_539
.LBB0_554:
	s_movk_i32 s41, 0xb00
	s_mov_b64 s[62:63], 0x400
	s_mov_b64 s[26:27], 0
	s_mov_b64 s[10:11], 0
	s_mov_b64 s[28:29], 0
	s_mov_b32 s48, s52
	s_mov_b64 s[34:35], 0
	s_andn2_b64 vcc, exec, s[88:89]
	s_cbranch_vccz .LBB0_529
	s_branch .LBB0_530

; __device__ __forceinline__ PItem p0_decode(const Args& a, int it) {
;     constexpr int I_IN = 16 * 96, I_OUT = 16 * 32, I_W1 = 16 * 88, I_W2 = 44 * 32, I_LAYER = I_IN + I_OUT + 2 * I_W1 + I_W2;
;     const int l = it / I_LAYER, e = l >> 1, odd = l & 1; int r = it % I_LAYER;
;     unsigned char* wl = a.ws + WS_W + (size_t)l * W_LAYER; float* cv = (float*)(a.ws + WS_CVEC) + (size_t)l * CVEC_LAYER;
;     PItem p;
;     if (r < I_IN) { const int kb = r / 96, nb = r % 96; p.W = (odd ? a.in[13] : a.in[5]) + (size_t)e * D * EIN; p.N = EIN; p.K = D; p.g = l > 0 ? a.in[21] + (size_t)(l - 1) * D : nullptr; p.be = l > 0 ? a.in[22] + (size_t)(l - 1) * D : nullptr;
;         p.WT = (bf16*)(wl + W_IN); p.drow0 = in_dst_row(32 * nb, odd); p.k0 = 64 * kb; p.n0 = 32 * nb; p.c1 = cv; p.c2 = cv + EIN; return p; } r -= I_IN;
;     if (r < I_OUT) { const int kb = r / 32, nb = r % 32; p.W = (odd ? a.in[15] : a.in[6]) + (size_t)e * D * D; p.N = D; p.K = D; p.g = nullptr; p.be = nullptr;
;         p.WT = (bf16*)(wl + W_OUT); p.drow0 = 32 * nb; p.k0 = 64 * kb; p.n0 = 32 * nb; p.c1 = nullptr; p.c2 = nullptr; return p; } r -= I_OUT;
;     if (r < 2 * I_W1) { const int second = r >= I_W1; if (second) r -= I_W1; const int kb = r / 88, nb = r % 88, n0 = 32 * nb; p.W = (second ? a.in[17] : a.in[16]) + (size_t)l * D * DFF; p.N = DFF; p.K = D;
;         p.g = a.in[19] + (size_t)l * D; p.be = a.in[20] + (size_t)l * D; p.WT = (bf16*)(wl + W_13); p.drow0 = 256 * (n0 >> 7) + (second ? 128 : 0) + (n0 & 127); p.k0 = 64 * kb; p.n0 = n0; p.c1 = cv + 2 * EIN; p.c2 = cv + 2 * EIN + NUP; return p; } r -= 2 * I_W1;
; __device__ __forceinline__ void p0_convert(const Frame& F, const Args& a, int it_lo, int it_hi, int widx, int nw, LAS float* scr) {
;     ...
;         for (int it = it0; it < itend; it += nw) {
;             const bool more = it + nw < itend;
;             PItem nxt = cur; f32x4 vn[8];
;             if (more) { nxt = p0_decode(a, it + nw); p0_item_load(nxt, F.lane, vn); }
.LBB0_1647:
	v_mov_b64_e32 v[64:65], v[28:29]
	v_readlane_b32 s64, v255, 16
	s_andn2_b64 vcc, exec, s[12:13]
	v_mov_b64_e32 v[62:63], v[26:27]
	s_mov_b64 s[18:19], s[30:31]
	s_mov_b64 s[20:21], s[60:61]
	s_mov_b32 s40, s2
	s_mov_b64 s[86:87], s[24:25]
	s_mov_b64 s[84:85], s[26:27]
	s_mov_b64 s[14:15], s[22:23]
	s_mov_b32 s12, s52
	s_mov_b32 s16, s66
	v_readlane_b32 s65, v255, 17
	s_cbranch_vccz .LBB0_1682
.LBB0_1648:
	v_add_u32_e32 v232, s16, v67
	v_ashrrev_i32_e32 v233, 31, v232
	v_mov_b32_e32 v230, 1.0
	v_mov_b32_e32 v231, 0
	s_cmp_eq_u64 s[86:87], 0
	s_cbranch_scc1 .Lcv_ng_fd2
	v_lshl_add_u64 v[234:235], v[232:233], 2, s[86:87]
	global_load_dword v230, v[234:235], off
.Lcv_ng_fd2:
	s_cmp_eq_u64 s[84:85], 0
	s_cbranch_scc1 .Lcv_nb_fd2
	v_lshl_add_u64 v[234:235], v[232:233], 2, s[84:85]
	global_load_dword v231, v[234:235], off
.Lcv_nb_fd2:
	s_add_i32 s29, s29, s41
	s_cmp_lt_i32 s29, s7
	s_cselect_b64 s[34:35], -1, 0
	s_cmp_ge_i32 s29, s7
	s_mov_b32 s52, s12
	s_mov_b32 s66, s16
	s_cbranch_scc1 .Lcv_np_fd2
	s_mul_hi_i32 s0, s29, 0x5397829d
	s_lshr_b32 s1, s0, 31
	s_ashr_i32 s0, s0, 11
	s_add_i32 s44, s0, s1
	s_mul_i32 s1, s44, 0x1880
	s_ashr_i32 s46, s44, 1
	s_and_b32 s0, s44, 1
	s_sub_i32 s1, s29, s1
	s_ashr_i32 s45, s44, 31
	s_mul_i32 s13, s44, 0x1880000
	v_readlane_b32 s17, v253, 5
	s_mul_hi_i32 s2, s44, 0x1880000
	s_add_u32 s64, s17, s13
	v_readlane_b32 s13, v253, 6
	s_addc_u32 s65, s13, s2
	s_mul_i32 s13, s44, 0x11000
	v_readlane_b32 s17, v253, 7
	s_mul_hi_i32 s2, s44, 0x11000
	s_add_u32 s56, s17, s13
	v_readlane_b32 s13, v253, 8
	s_addc_u32 s57, s13, s2
	s_cmpk_gt_i32 s1, 0x5ff
	s_mov_b64 s[88:89], -1
	s_cbranch_scc0 .LBB0_1658
	s_cmpk_gt_u32 s1, 0x7ff
	s_cbranch_scc0 .LBB0_1655
	s_mov_b64 s[24:25], -1
	s_cmpk_gt_u32 s1, 0x12ff
	s_mul_hi_i32 s2, s44, 0xb00000
	s_mul_i32 s13, s44, 0xb00000
	s_cbranch_scc0 .LBB0_1653
	v_readlane_b32 s76, v253, 26
	v_readlane_b32 s77, v253, 27
	s_add_u32 s58, s76, s13
	s_addc_u32 s59, s77, s2
	s_add_u32 s22, s64, 0x1300000
	s_addc_u32 s23, s65, 0
	s_lshl_b32 s17, s1, 5
	s_and_b32 s52, s17, 0x3e0
	s_lshl_b32 s17, s1, 1
	s_and_b32 s17, s17, 0x7fffffc0
	v_readlane_b32 s78, v253, 28
	v_readlane_b32 s79, v253, 29
	v_readlane_b32 s80, v253, 30
	v_readlane_b32 s81, v253, 31
	v_readlane_b32 s82, v253, 32
	v_readlane_b32 s83, v253, 33
	s_add_i32 s66, s17, 0xffffda00
	s_mov_b64 s[24:25], 0

; #define GAS __attribute__((address_space(1)))
; #define LAS __attribute__((address_space(3)))
; #define LDS_WAIT() asm volatile("s_waitcnt lgkmcnt(0)" ::: "memory")
; __device__ __forceinline__ void p0_item_load(const PItem& it, int lane, f32x4 (&v)[8]) {
; #pragma unroll
;     for (int i = 0; i < 8; ++i) v[i] = __builtin_nontemporal_load((const GAS f32x4*)(it.W + (size_t)(it.k0 + 8 * i + (lane >> 3)) * it.N + it.n0 + 4 * (lane & 7)));
; }
; __device__ __forceinline__ void p0_item_process(const PItem& it, int lane, const f32x4 (&v)[8], LAS float* scr) {
;     LAS float* gl = scr + 64 * 36 + 32; LAS float* bl = gl + 64;
;     ...
; #pragma unroll
;     for (int i = 0; i < 8; ++i) *(LAS f32x4*)(scr + SCR_ROW(8 * i + (lane >> 3)) + 4 * (lane & 7)) = v[i];
;     gl[lane] = it.g ? it.g[it.k0 + lane] : 1.f; bl[lane] = it.be ? it.be[it.k0 + lane] : 0.f;
;     LDS_WAIT(); asm volatile("" ::: "memory");
;     if (it.c1) { const int n = lane & 31, kh = lane >> 5; float s1 = 0.f, s2 = 0.f;
.LBB0_1665:
	v_add_u32_e32 v2, s66, v70
	v_add_u32_e32 v10, s66, v72
	v_add_u32_e32 v18, s66, v74
	v_add_u32_e32 v26, s66, v76
	v_ashrrev_i32_e32 v3, 31, v2
	v_ashrrev_i32_e32 v11, 31, v10
	v_ashrrev_i32_e32 v19, 31, v18
	v_ashrrev_i32_e32 v27, 31, v26
	v_mul_lo_u32 v4, s48, v3
	v_mul_lo_u32 v5, s49, v2
	v_mad_u64_u32 v[2:3], s[0:1], s48, v2, 0
	v_mul_lo_u32 v12, s48, v11
	v_mul_lo_u32 v13, s49, v10
	v_mad_u64_u32 v[10:11], s[44:45], s48, v10, 0
	v_mul_lo_u32 v20, s48, v19
	v_mul_lo_u32 v21, s49, v18
	v_mad_u64_u32 v[18:19], s[44:45], s48, v18, 0
	v_mul_lo_u32 v28, s48, v27
	v_mul_lo_u32 v29, s49, v26
	v_mad_u64_u32 v[26:27], s[44:45], s48, v26, 0
	v_add3_u32 v3, v3, v4, v5
	v_add_u32_e32 v4, s66, v71
	v_add3_u32 v11, v11, v12, v13
	v_add_u32_e32 v12, s66, v73
	v_add3_u32 v19, v19, v20, v21
	v_add_u32_e32 v20, s66, v75
	v_add3_u32 v27, v27, v28, v29
	v_add_u32_e32 v28, s66, v77
	v_ashrrev_i32_e32 v5, 31, v4
	v_ashrrev_i32_e32 v13, 31, v12
	v_ashrrev_i32_e32 v21, 31, v20
	v_ashrrev_i32_e32 v29, 31, v28
	v_mul_lo_u32 v6, s48, v5
	v_mul_lo_u32 v7, s49, v4
	v_mad_u64_u32 v[4:5], s[44:45], s48, v4, 0
	v_mul_lo_u32 v14, s48, v13
	v_mul_lo_u32 v15, s49, v12
	v_mad_u64_u32 v[12:13], s[44:45], s48, v12, 0
	v_mul_lo_u32 v22, s48, v21
	v_mul_lo_u32 v23, s49, v20
	v_mad_u64_u32 v[20:21], s[44:45], s48, v20, 0
	v_mul_lo_u32 v30, s48, v29
	v_mul_lo_u32 v31, s49, v28
	v_mad_u64_u32 v[28:29], s[44:45], s48, v28, 0
	s_ashr_i32 s63, s62, 31
	v_add3_u32 v5, v5, v6, v7
	v_add3_u32 v13, v13, v14, v15
	v_add3_u32 v21, v21, v22, v23
	v_add3_u32 v29, v29, v30, v31
	v_lshl_add_u64 v[2:3], v[2:3], 2, s[58:59]
	s_lshl_b64 s[0:1], s[62:63], 2
	v_lshl_add_u64 v[4:5], v[4:5], 2, s[58:59]
	v_lshl_add_u64 v[10:11], v[10:11], 2, s[58:59]
	v_lshl_add_u64 v[12:13], v[12:13], 2, s[58:59]
	v_lshl_add_u64 v[18:19], v[18:19], 2, s[58:59]
	v_lshl_add_u64 v[20:21], v[20:21], 2, s[58:59]
	v_lshl_add_u64 v[26:27], v[26:27], 2, s[58:59]
	v_lshl_add_u64 v[28:29], v[28:29], 2, s[58:59]
	v_lshl_add_u64 v[2:3], v[2:3], 0, s[0:1]
	v_mov_b32_e32 v69, v1
	v_lshl_add_u64 v[4:5], v[4:5], 0, s[0:1]
	v_lshl_add_u64 v[10:11], v[10:11], 0, s[0:1]
	v_lshl_add_u64 v[12:13], v[12:13], 0, s[0:1]
	v_lshl_add_u64 v[18:19], v[18:19], 0, s[0:1]
	v_lshl_add_u64 v[20:21], v[20:21], 0, s[0:1]
	v_lshl_add_u64 v[26:27], v[26:27], 0, s[0:1]
	v_lshl_add_u64 v[28:29], v[28:29], 0, s[0:1]
	v_lshl_add_u64 v[2:3], v[2:3], 0, v[68:69]
	v_lshl_add_u64 v[4:5], v[4:5], 0, v[68:69]
	v_lshl_add_u64 v[10:11], v[10:11], 0, v[68:69]
	v_lshl_add_u64 v[12:13], v[12:13], 0, v[68:69]
	v_lshl_add_u64 v[18:19], v[18:19], 0, v[68:69]
	v_lshl_add_u64 v[20:21], v[20:21], 0, v[68:69]
	v_lshl_add_u64 v[26:27], v[26:27], 0, v[68:69]
	v_lshl_add_u64 v[28:29], v[28:29], 0, v[68:69]
	global_load_dwordx4 v[6:9], v[2:3], off nt
	s_nop 0
	global_load_dwordx4 v[2:5], v[4:5], off nt
	s_nop 0
	global_load_dwordx4 v[14:17], v[10:11], off nt
	s_nop 0
	global_load_dwordx4 v[10:13], v[12:13], off nt
	s_nop 0
	global_load_dwordx4 v[22:25], v[18:19], off nt
	s_nop 0
	global_load_dwordx4 v[18:21], v[20:21], off nt
	s_nop 0
	global_load_dwordx4 v[30:33], v[26:27], off nt
	s_nop 0
	global_load_dwordx4 v[26:29], v[28:29], off nt
.LBB0_1666:
	s_waitcnt vmcnt(15)
	ds_write_b128 v78, v[58:61]
	s_waitcnt vmcnt(14)
	ds_write_b128 v79, v[42:45] offset:16
	s_waitcnt vmcnt(13)
	ds_write_b128 v80, v[54:57] offset:32
	s_waitcnt vmcnt(12)
	ds_write_b128 v81, v[38:41] offset:48
	s_waitcnt vmcnt(11)
	ds_write_b128 v82, v[50:53] offset:64
	s_waitcnt vmcnt(10)
	ds_write_b128 v83, v[34:37] offset:80
	s_waitcnt vmcnt(9)
	ds_write_b128 v84, v[46:49] offset:96
	s_waitcnt vmcnt(8)
	ds_write_b128 v85, v[62:65] offset:112
	s_cmp_lg_u64 s[84:85], 0
	s_cselect_b64 s[64:65], -1, 0
	s_waitcnt vmcnt(8)
	ds_write_b32 v86, v230 offset:9344
	ds_write_b32 v86, v231 offset:9600
	s_waitcnt lgkmcnt(0)
	s_cmp_eq_u64 s[20:21], 0
	s_cbranch_scc1 .LBB0_1679
	v_mov_b32_e32 v34, 0
	s_mov_b32 s0, 0
	v_mov_b32_e32 v36, v90
	v_mov_b32_e32 v35, v34

; #define LAS __attribute__((address_space(3)))
; __device__ __forceinline__ PItem p0_decode(const Args& a, int it) {
;     ...
;     { const int kb = r / 32, nb = r % 32; p.W = a.in[18] + (size_t)l * DFF * D; p.N = D; p.K = DFF; p.g = nullptr; p.be = nullptr; p.WT = (bf16*)(wl + W_2); p.drow0 = 32 * nb; p.k0 = 64 * kb; p.n0 = 32 * nb; p.c1 = nullptr; p.c2 = nullptr; return p; }
; }
; __device__ __forceinline__ void p0_convert(const Frame& F, const Args& a, int it_lo, int it_hi, int widx, int nw, LAS float* scr) {
;     const int it0 = it_lo + widx, itend = it_hi;
;     if (it0 < itend) {
;         PItem cur = p0_decode(a, it0); f32x4 vc[8]; p0_item_load(cur, F.lane, vc);
;         for (int it = it0; it < itend; it += nw) {
;             const bool more = it + nw < itend;
;             PItem nxt = cur; f32x4 vn[8];
;             if (more) { nxt = p0_decode(a, it + nw); p0_item_load(nxt, F.lane, vn); }
;             p0_item_process(cur, F.lane, vc, scr);
.Lcv_np_fd2:
	s_waitcnt vmcnt(0)
	s_branch .LBB0_1666
.LBB0_1681:
	s_movk_i32 s2, 0xb00
	s_mov_b64 s[48:49], 0x400
	s_mov_b64 s[30:31], 0
	s_mov_b64 s[24:25], 0
	s_mov_b64 s[26:27], 0
	s_mov_b32 s62, s52
	s_mov_b64 s[60:61], 0
	s_andn2_b64 vcc, exec, s[88:89]
	s_cbranch_vccz .LBB0_1656
	s_branch .LBB0_1657
